# scan O output: v_permlane32_swap pairs + 2 dwordx4 stores per chunk instead of 4 dwordx2 (docs 7.3 store widening)
# baseline (speedup 1.0000x reference)
; DEV int tidx() { return tidx_full() & 255; }
; DEV void scan_item_mfma(const Params& p, int g, int item, char* smem) {
;     ...
;   const int tid = tidx();
;   const int wave = __builtin_amdgcn_readfirstlane(tid >> 6);
;   const int lane = tid & 63, r = lane & 31, hh = lane >> 5;
;   __syncthreads();
;   for (int e = tid; e < 8704 / 16; e += 256) ((uint4*)Sts)[e] = make_uint4(0, 0, 0, 0);
;   f32x16 accS[2];
; #pragma unroll
;   for (int t = 0; t < 2; ++t)
; #pragma unroll
;     for (int i = 0; i < 16; ++i) accS[t][i] = 0.f;
;   const int ocol = (dir ? 1024 : 0) + h * 128 + vs * 32;
;   uint4 q0, q1, q2, q3, k0, k1, k2, k3, t0, t1, t2, t3, vv;
;   float dd = 0.f;
;   const int qrow = tid >> 4, qc = tid & 15;
;   const int trow = tid >> 3, tc = tid & 7;
;   const int vrow = tid >> 2, vc = tid & 3;
; DEV void phase_p2_naive(const Params& p, int g, char* hsm) {
;     ...
;   if ((int)blockIdx.x * 2 < nscan) scan_item_mfma(p, g, blockIdx.x * 2 + half, hsm);
.LBB0_667:
	s_movk_i32 s40, 0x1400
	s_or_b64 exec, exec, s[0:1]
	s_and_b64 s[0:1], s[66:67], exec
	v_readfirstlane_b32 s24, v202
	s_cselect_b32 s0, 0x100, s61
	s_lshr_b32 s26, s24, 8
	s_cmp_ge_i32 s81, s0
	s_waitcnt lgkmcnt(0)
	s_barrier
	s_cbranch_scc1 .LBB0_720
	v_writelane_b32 v160, s0, 0
	v_writelane_b32 v160, s1, 1
	v_writelane_b32 v160, s2, 2
	v_writelane_b32 v160, s3, 3
	v_writelane_b32 v160, s4, 4
	v_writelane_b32 v160, s5, 5
	v_writelane_b32 v160, s6, 6
	v_writelane_b32 v160, s7, 7
	v_writelane_b32 v160, s8, 8
	v_writelane_b32 v160, s9, 9
	v_writelane_b32 v160, s10, 10
	v_writelane_b32 v160, s11, 11
	v_writelane_b32 v160, s12, 12
	v_writelane_b32 v160, s13, 13
	v_writelane_b32 v160, s14, 14
	v_writelane_b32 v160, s15, 15
	v_writelane_b32 v160, s16, 16
	v_writelane_b32 v160, s17, 17
	v_writelane_b32 v160, s18, 18
	v_writelane_b32 v160, s19, 19
	v_writelane_b32 v160, s20, 20
	v_writelane_b32 v160, s21, 21
	v_writelane_b32 v160, s22, 22
	v_writelane_b32 v160, s23, 23
	v_writelane_b32 v160, s24, 24
	v_writelane_b32 v160, s25, 25
	v_writelane_b32 v160, s26, 26
	v_writelane_b32 v160, s27, 27
	v_writelane_b32 v160, s28, 28
	v_writelane_b32 v160, s29, 29
	v_writelane_b32 v160, s30, 30
	v_writelane_b32 v160, s31, 31
	v_writelane_b32 v160, s33, 33
	v_writelane_b32 v160, s34, 34
	v_writelane_b32 v160, s35, 35
	v_writelane_b32 v160, s36, 36
	v_writelane_b32 v160, s37, 37
	v_writelane_b32 v160, s38, 38
	v_writelane_b32 v160, s39, 39
	v_writelane_b32 v160, s40, 40
	v_writelane_b32 v160, s41, 41
	v_writelane_b32 v160, s42, 42
	v_writelane_b32 v160, s43, 43
	v_writelane_b32 v160, s44, 44
	v_writelane_b32 v160, s45, 45
	v_writelane_b32 v160, s46, 46
	v_writelane_b32 v160, s47, 47
	v_writelane_b32 v160, s48, 48
	v_writelane_b32 v160, s49, 49
	v_writelane_b32 v160, s50, 50
	v_writelane_b32 v160, s51, 51
	v_writelane_b32 v160, s52, 52
	v_writelane_b32 v160, s53, 53
	v_writelane_b32 v160, s54, 54
	v_writelane_b32 v160, s55, 55
	v_writelane_b32 v160, s56, 56
	v_writelane_b32 v160, s57, 57
	v_writelane_b32 v160, s58, 58
	v_writelane_b32 v160, s59, 59
	v_writelane_b32 v160, s60, 60
	v_writelane_b32 v160, s61, 61
	v_writelane_b32 v160, s62, 62
	v_writelane_b32 v160, s63, 63
	v_writelane_b32 v161, s64, 0
	v_writelane_b32 v161, s65, 1
	v_writelane_b32 v161, s66, 2
	v_writelane_b32 v161, s67, 3
	v_writelane_b32 v161, s68, 4
	v_writelane_b32 v161, s69, 5
	v_writelane_b32 v161, s70, 6
	v_writelane_b32 v161, s71, 7
	v_writelane_b32 v161, s72, 8
	v_writelane_b32 v161, s73, 9
	s_barrier
	s_add_i32 s2, s26, s81
	s_and_b32 s3, s2, 3
	s_bfe_u32 s4, s2, 0x10002
	s_bfe_u32 s5, s2, 0x20003
	s_lshr_b32 s6, s2, 5
	s_and_b64 s[0:1], s[66:67], exec
	s_cselect_b32 s7, 64, 0x80
	s_bfe_u32 s9, s24, 0x20006
	s_mul_i32 s31, s26, 0x3600
	s_add_u32 s31, s31, 0xf400
	v_and_b32_e32 v53, 0xff, v202
	v_and_b32_e32 v54, 63, v202
	v_and_b32_e32 v55, 31, v202
	v_bfe_u32 v109, v202, 5, 1
	v_bfe_u32 v110, v202, 6, 2
	v_and_b32_e32 v111, 0x1ff, v202
	v_lshrrev_b32_e32 v220, 4, v111
	v_and_b32_e32 v221, 15, v111
	v_lshlrev_b32_e32 v219, 4, v221
	v_lshl_add_u32 v209, v220, 10, v219
	v_add_u32_e32 v210, 0x8000, v209
	v_mul_u32_u24_e32 v248, 0x110, v220
	v_add_u32_e32 v234, v248, v219
	v_lshrrev_b32_e32 v220, 3, v111
	v_and_b32_e32 v221, 7, v111
	v_lshlrev_b32_e32 v219, 4, v221
	v_lshl_add_u32 v213, v220, 7, v219
	v_add_u32_e32 v214, 0x2000, v213
	v_mul_u32_u24_e32 v248, 0x90, v220
	v_add_u32_e32 v235, v248, v219
	v_lshrrev_b32_e32 v220, 2, v53
	v_and_b32_e32 v221, 3, v53
	v_mul_u32_u24_e32 v219, 0x1400, v220
	v_lshl_add_u32 v215, v221, 4, v219
	v_mul_u32_u24_e32 v219, 0x480, v221
	v_lshl_add_u32 v219, v220, 1, v219
	v_add_u32_e32 v236, s31, v219
	v_and_b32_e32 v220, 0x7f, v53
	v_lshlrev_b32_e32 v216, 2, v220
	v_add_u32_e32 v237, s31, v216
	v_mul_u32_u24_e32 v220, 0x110, v55
	v_mul_u32_u24_e32 v221, 0x90, v55
	v_lshlrev_b32_e32 v219, 4, v109
	v_add_u32_e32 v164, v220, v219
	v_add3_u32 v245, v220, v219, s31
	v_add3_u32 v244, v221, v219, s31
	v_add_u32_e32 v111, v221, v219
	v_lshrrev_b32_e32 v248, 1, v110
	v_mul_u32_u24_e32 v248, 0x2200, v248
	v_add_u32_e32 v240, v164, v248
	v_and_b32_e32 v248, 1, v110
	v_mul_u32_u24_e32 v248, 0x2200, v248
	v_add_u32_e32 v242, v164, v248
	v_mul_u32_u24_e32 v248, 0x2200, v110
	v_add_u32_e32 v241, v164, v248
	v_mul_u32_u24_e32 v248, 0x1200, v110
	v_add_u32_e32 v243, v111, v248
	v_lshrrev_b32_e32 v248, 1, v110
	v_mul_u32_u24_e32 v248, 0x1200, v248
	v_add_u32_e32 v239, v221, v248
	v_and_b32_e32 v248, 1, v110
	v_lshlrev_b32_e32 v248, 6, v248
	v_lshl_add_u32 v248, v109, 3, v248
	v_add_u32_e32 v239, v239, v248
	v_subrev_u32_e32 v248, 2, v110
	v_lshlrev_b32_e32 v219, 7, v248
	v_lshl_add_u32 v219, v109, 3, v219
	v_add3_u32 v238, v220, v219, s31
	v_mul_u32_u24_e32 v219, 0x2400, v248
	v_add_u32_e32 v207, v111, v219
	v_lshlrev_b32_e32 v219, 8, v248
	v_lshl_add_u32 v219, v109, 4, v219
	v_add_u32_e32 v208, s31, v219
	v_lshl_add_u32 v219, v110, 5, v55
	v_mul_u32_u24_e32 v219, 0x1400, v219
	v_lshl_add_u32 v217, v109, 4, v219
	v_lshlrev_b32_e32 v219, 2, v109
	v_sub_u32_e32 v218, v55, v219
	s_cmp_eq_u32 s4, 0
	s_cbranch_scc0 .Lscan_d1
; DEV void scan_item_mfma(const Params& p, int g, int item, char* smem) {
;     ...
;   for (int e = tid; e < 8704 / 16; e += 256) ((uint4*)Sts)[e] = make_uint4(0, 0, 0, 0);
;   f32x16 accS[2];
; #pragma unroll
;   for (int t = 0; t < 2; ++t)
; #pragma unroll
;     for (int i = 0; i < 16; ++i) accS[t][i] = 0.f;
;   const int ocol = (dir ? 1024 : 0) + h * 128 + vs * 32;
;   uint4 q0, q1, q2, q3, k0, k1, k2, k3, t0, t1, t2, t3, vv;
;   float dd = 0.f;
;   const int qrow = tid >> 4, qc = tid & 15;
;   const int trow = tid >> 3, tc = tid & 7;
;   const int vrow = tid >> 2, vc = tid & 3;
;     ...
;   unsigned opk[8] = {0u, 0u, 0u, 0u, 0u, 0u, 0u, 0u};
;   size_t otok = 0;
;   SCAN_ISSUE(dir ? NC - 1 : 0);
	s_mul_i32 s11, s6, s7
	s_mov_b32 s12, s64
	s_mov_b32 s13, s65
	s_mul_i32 s0, s11, 0x10000
	s_add_u32 s12, s12, s0
	s_addc_u32 s13, s13, 0
	s_mul_i32 s0, s5, 0x100
	s_add_u32 s12, s12, s0
	s_addc_u32 s13, s13, 0
	s_add_u32 s14, s12, 0x2000000
	s_addc_u32 s15, s13, 0
	s_add_u32 s16, s88, 0x3d4c100
	s_addc_u32 s17, s89, 0
	s_mul_i32 s0, s11, 0x20000
	s_add_u32 s16, s16, s0
	s_addc_u32 s17, s17, 0
	s_mul_i32 s0, s5, 0x4000
	s_add_u32 s16, s16, s0
	s_addc_u32 s17, s17, 0
	s_add_u32 s18, s88, 0xdd4c500
	s_addc_u32 s19, s89, 0
	s_mul_i32 s0, s11, 0x50000
	s_add_u32 s18, s18, s0
	s_addc_u32 s19, s19, 0
	s_mul_i32 s0, s5, 0x100
	s_add_u32 s18, s18, s0
	s_addc_u32 s19, s19, 0
	s_mul_i32 s0, s3, 0x40
	s_add_u32 s18, s18, s0
	s_addc_u32 s19, s19, 0
	s_add_u32 s20, s88, 0x3b4c100
	s_addc_u32 s21, s89, 0
	s_mul_i32 s0, s11, 0x800
	s_add_u32 s20, s20, s0
	s_addc_u32 s21, s21, 0
	s_mul_i32 s0, s5, 0x200
	s_add_u32 s20, s20, s0
	s_addc_u32 s21, s21, 0
	s_add_u32 s22, s88, 0xdd4c100
	s_addc_u32 s23, s89, 0
	s_mul_i32 s0, s11, 0x50000
	s_add_u32 s22, s22, s0
	s_addc_u32 s23, s23, 0
	s_mul_i32 s0, s5, 0x100
	s_add_u32 s22, s22, s0
	s_addc_u32 s23, s23, 0
	s_mul_i32 s0, s3, 0x40
	s_add_u32 s22, s22, s0
	s_addc_u32 s23, s23, 0
	v_cmp_le_i32_e64 s[34:35], 0, v218
	v_cmp_le_i32_e64 s[36:37], 1, v218
	v_cmp_le_i32_e64 s[38:39], 2, v218
	v_cmp_le_i32_e64 s[40:41], 3, v218
	v_cmp_le_i32_e64 s[42:43], 8, v218
	v_cmp_le_i32_e64 s[44:45], 9, v218
	v_cmp_le_i32_e64 s[46:47], 10, v218
	v_cmp_le_i32_e64 s[48:49], 11, v218
	v_cmp_le_i32_e64 s[50:51], 16, v218
	v_cmp_le_i32_e64 s[52:53], 17, v218
	v_cmp_le_i32_e64 s[54:55], 18, v218
	v_cmp_le_i32_e64 s[56:57], 19, v218
	v_cmp_le_i32_e64 s[58:59], 24, v218
	v_cmp_le_i32_e64 s[60:61], 25, v218
	v_cmp_le_i32_e64 s[62:63], 26, v218
	v_cmp_le_i32_e64 s[64:65], 27, v218
	v_mov_b32_e32 v144, 0
	v_mov_b32_e32 v145, 0
	v_mov_b32_e32 v146, 0
	v_mov_b32_e32 v147, 0
	v_mov_b64_e32 v[112:113], v[144:145]
	v_mov_b64_e32 v[114:115], v[144:145]
	v_mov_b64_e32 v[116:117], v[144:145]
	v_mov_b64_e32 v[118:119], v[144:145]
	v_mov_b64_e32 v[120:121], v[144:145]
	v_mov_b64_e32 v[122:123], v[144:145]
	v_mov_b64_e32 v[124:125], v[144:145]
	v_mov_b64_e32 v[126:127], v[144:145]
	v_mov_b64_e32 v[128:129], v[144:145]
	v_mov_b64_e32 v[130:131], v[144:145]
	v_mov_b64_e32 v[132:133], v[144:145]
	v_mov_b64_e32 v[134:135], v[144:145]
	v_mov_b64_e32 v[136:137], v[144:145]
	v_mov_b64_e32 v[138:139], v[144:145]
	v_mov_b64_e32 v[140:141], v[144:145]
	v_mov_b64_e32 v[142:143], v[144:145]
	v_lshl_add_u32 v220, v53, 5, s31
	ds_write_b128 v220, v[144:147] offset:4608
	ds_write_b128 v220, v[144:147] offset:4624
	v_and_b32_e32 v221, 31, v53
	v_lshl_add_u32 v221, v221, 4, s31
	ds_write_b128 v221, v[144:147] offset:12800
	s_cmp_eq_u32 s26, 1
	s_cbranch_scc0 .Lsc0_nz
	s_cmp_eq_u32 s9, 1
	s_cbranch_scc0 .Lsc0_nz
	v_mul_u32_u24_e32 v219, 24, v109
	v_add_u32_e32 v219, v239, v219
	ds_write_b128 v219, v[144:147] offset:53248
	ds_write_b128 v219, v[144:147] offset:53264

; DEV void scan_item_mfma(const Params& p, int g, int item, char* smem) {
;     ...
;         u16* og = PHG + (otok + 32 * wave + 4 * hh) * 2560 + ocol + r;
; #pragma unroll
;         for (int i = 0; i < 8; ++i) {
;           og[(size_t)(((2 * i) & 3) + 8 * ((2 * i) >> 2)) * 2560] = (u16)(opk[i] & 0xffffu);
;           og[(size_t)(((2 * i + 1) & 3) + 8 * ((2 * i + 1) >> 2)) * 2560] = (u16)(opk[i] >> 16);
;         }
;     ...
;     if (wave < 2) {
;       const int jt = wave;
;       bf16x8 pp[4], vb[4], qa[4], sb[4];
; #pragma unroll
;       for (int ks = 0; ks < 4; ++ks) {
;         pp[ks] = *(const bf16x8*)(Ps + (32 * jt + r) * 144 + ks * 32 + hh * 16);
;         vb[ks] = *(const bf16x8*)(Vts + r * 144 + ks * 32 + hh * 16);
;         qa[ks] = *(const bf16x8*)(Qs + (32 * jt + r) * 272 + ks * 32 + hh * 16);
;         sb[ks] = *(const bf16x8*)(Sts + r * 272 + ks * 32 + hh * 16);
;       }
;       __builtin_amdgcn_sched_barrier(0);
;       f32x16 o, o1;
; #pragma unroll
;       for (int i = 0; i < 16; ++i) { o[i] = 0.f; o1[i] = 0.f; }
; #pragma unroll
;       for (int ks = 0; ks < 4; ++ks) {
;         o = __builtin_amdgcn_mfma_f32_32x32x16_bf16(pp[ks], vb[ks], o, 0, 0, 0);
;         o1 = __builtin_amdgcn_mfma_f32_32x32x16_bf16(qa[ks], sb[ks], o1, 0, 0, 0);
;       }
;       __builtin_amdgcn_sched_barrier(0);
; #pragma unroll
;       for (int ks = 0; ks < 4; ++ks) {
;         qa[ks] = *(const bf16x8*)(Qs + (32 * jt + r) * 272 + (ks + 4) * 32 + hh * 16);
;         sb[ks] = *(const bf16x8*)(Sts + r * 272 + (ks + 4) * 32 + hh * 16);
;       }
;       __builtin_amdgcn_sched_barrier(0);
;       o = __builtin_amdgcn_mfma_f32_32x32x16_bf16(qa[0], sb[0], o, 0, 0, 0);
;       o1 = __builtin_amdgcn_mfma_f32_32x32x16_bf16(qa[1], sb[1], o1, 0, 0, 0);
;       o = __builtin_amdgcn_mfma_f32_32x32x16_bf16(qa[2], sb[2], o, 0, 0, 0);
;       o1 = __builtin_amdgcn_mfma_f32_32x32x16_bf16(qa[3], sb[3], o1, 0, 0, 0);
;       f32x16 o2;
; #pragma unroll
;       for (int i = 0; i < 16; ++i) o2[i] = 0.f;
; #pragma unroll
;       for (int i = 0; i < 8; ++i)
;         opk[i] = pack2(o[2 * i] + o1[2 * i] + o2[2 * i], o[2 * i + 1] + o1[2 * i + 1] + o2[2 * i + 1]);
.Lsc0_p2efa:
	s_waitcnt lgkmcnt(0)
	s_barrier
	s_cmp_lt_u32 s9, 2
	s_cbranch_scc0 .Lsc0_p3sfa
	ds_read_b128 v[166:169], v243 offset:53248
	ds_read_b128 v[170:173], v243 offset:53280
	ds_read_b128 v[174:177], v243 offset:53312
	ds_read_b128 v[178:181], v243 offset:53344
	ds_read_b128 v[182:185], v244
	ds_read_b128 v[186:189], v244 offset:32
	ds_read_b128 v[190:193], v244 offset:64
	ds_read_b128 v[194:197], v244 offset:96
	ds_read_b128 v[198:201], v241
	ds_read_b128 v[222:225], v241 offset:32
	ds_read_b128 v[226:229], v241 offset:64
	ds_read_b128 v[230:233], v241 offset:96
	s_waitcnt lgkmcnt(4)
	v_mfma_f32_32x32x16_bf16 v[112:127], v[182:185], v[166:169], 0
	v_mfma_f32_32x32x16_bf16 v[112:127], v[186:189], v[170:173], v[112:127]
	v_mfma_f32_32x32x16_bf16 v[112:127], v[190:193], v[174:177], v[112:127]
	v_mfma_f32_32x32x16_bf16 v[112:127], v[194:197], v[178:181], v[112:127]
	ds_read_b128 v[166:169], v245 offset:4608
	ds_read_b128 v[170:173], v245 offset:4640
	ds_read_b128 v[174:177], v245 offset:4672
	ds_read_b128 v[178:181], v245 offset:4704
	s_waitcnt lgkmcnt(0)
	v_mfma_f32_32x32x16_bf16 v[112:127], v[166:169], v[198:201], v[112:127]
	v_mfma_f32_32x32x16_bf16 v[112:127], v[170:173], v[222:225], v[112:127]
	v_mfma_f32_32x32x16_bf16 v[112:127], v[174:177], v[226:229], v[112:127]
	v_mfma_f32_32x32x16_bf16 v[112:127], v[178:181], v[230:233], v[112:127]
	ds_read_b128 v[198:201], v241 offset:128
	ds_read_b128 v[222:225], v241 offset:160
	ds_read_b128 v[226:229], v241 offset:192
	ds_read_b128 v[230:233], v241 offset:224
	ds_read_b128 v[182:185], v245 offset:4736
	ds_read_b128 v[186:189], v245 offset:4768
	ds_read_b128 v[190:193], v245 offset:4800
	ds_read_b128 v[194:197], v245 offset:4832
	s_waitcnt lgkmcnt(0)
	v_mfma_f32_32x32x16_bf16 v[112:127], v[182:185], v[198:201], v[112:127]
	v_mfma_f32_32x32x16_bf16 v[112:127], v[186:189], v[222:225], v[112:127]
	v_mfma_f32_32x32x16_bf16 v[112:127], v[190:193], v[226:229], v[112:127]
	v_mfma_f32_32x32x16_bf16 v[112:127], v[194:197], v[230:233], v[112:127]
	s_nop 7
	s_nop 7
	v_cvt_pk_bf16_f32 v112, v112, v113
	v_cvt_pk_bf16_f32 v113, v114, v115
	v_cvt_pk_bf16_f32 v114, v116, v117
	v_cvt_pk_bf16_f32 v115, v118, v119
	v_cvt_pk_bf16_f32 v116, v120, v121
	v_cvt_pk_bf16_f32 v117, v122, v123
	v_cvt_pk_bf16_f32 v118, v124, v125
	v_cvt_pk_bf16_f32 v119, v126, v127
	s_nop 1
	v_permlane32_swap_b32 v112, v114
	v_permlane32_swap_b32 v113, v115
	v_permlane32_swap_b32 v116, v118
	v_permlane32_swap_b32 v117, v119
	global_store_dwordx4 v217, v[112:115], s[22:23]
	global_store_dwordx4 v217, v[116:119], s[22:23] offset:32
	s_branch .Lsc0_p3efa

; #define SCAN_BAR()                                        \
;   {                                                       \
;     asm volatile("s_waitcnt lgkmcnt(0)" ::: "memory");     \
;     __builtin_amdgcn_s_barrier();                         \
;     asm volatile("" ::: "memory");                         \
;   }
; DEV void scan_item_mfma(const Params& p, int g, int item, char* smem) {
;     ...
;       if (wave < 2 && ci > 0) {
;         u16* og = PHG + (otok + 32 * wave + 4 * hh) * 2560 + ocol + r;
; #pragma unroll
;         for (int i = 0; i < 8; ++i) {
;           og[(size_t)(((2 * i) & 3) + 8 * ((2 * i) >> 2)) * 2560] = (u16)(opk[i] & 0xffffu);
;           og[(size_t)(((2 * i + 1) & 3) + 8 * ((2 * i + 1) >> 2)) * 2560] = (u16)(opk[i] >> 16);
;         }
;     ...
;     SCAN_BAR();
;   }
.Lsc0_p3efa:
	s_mov_b32 s0, 0x50000
	s_add_u32 s22, s22, s0
	s_addc_u32 s23, s23, 0
	s_waitcnt lgkmcnt(0)
	s_barrier
	s_cmp_lt_u32 s9, 2
	s_cbranch_scc0 .Lsc0_w1sfb
	s_waitcnt vmcnt(10)
	s_branch .Lsc0_w1efb

; DEV void scan_item_mfma(const Params& p, int g, int item, char* smem) {
;     ...
;   for (int ci = 0; ci < NC; ++ci) {
;     const int n = dir ? NC - 1 - ci : ci;
;     const size_t tok0 = ((size_t)b * NC + n) * 64;
;     {
;       char* d = Qs + qrow * 272 + qc * 16;
;       *(uint4*)(d) = q0; *(uint4*)(d + 16 * 272) = q1; *(uint4*)(d + 32 * 272) = q2; *(uint4*)(d + 48 * 272) = q3;
;       d = Ks + qrow * 272 + qc * 16;
;       *(uint4*)(d) = k0; *(uint4*)(d + 16 * 272) = k1; *(uint4*)(d + 32 * 272) = k2; *(uint4*)(d + 48 * 272) = k3;
;       d = KTs + trow * 144 + tc * 16;
;       *(uint4*)(d) = t0; *(uint4*)(d + 32 * 144) = t1; *(uint4*)(d + 64 * 144) = t2; *(uint4*)(d + 96 * 144) = t3;
;       st8t(Vts + (vc * 8) * 144 + vrow * 2, vv);
;       if (tid < 128) decs[tid] = dd;
;       if (wave < 2 && ci > 0) {
;         u16* og = PHG + (otok + 32 * wave + 4 * hh) * 2560 + ocol + r;
.Lsc0_loop:
	s_cmp_lt_u32 s9, 2
	s_cbranch_scc0 .Lsc0_w1sa
	s_waitcnt vmcnt(12)
	s_branch .Lsc0_w1ea

; #define SCAN_BAR()                                        \
;   {                                                       \
;     asm volatile("s_waitcnt lgkmcnt(0)" ::: "memory");     \
;     __builtin_amdgcn_s_barrier();                         \
;     asm volatile("" ::: "memory");                         \
;   }
; DEV void scan_item_mfma(const Params& p, int g, int item, char* smem) {
;     ...
;   for (int ci = 0; ci < NC; ++ci) {
;     ...
;     SCAN_BAR();
;   }
.Lsc0_p3eb:
	s_mov_b32 s0, 0x50000
	s_add_u32 s22, s22, s0
	s_addc_u32 s23, s23, 0
	s_waitcnt lgkmcnt(0)
	s_barrier
	s_sub_i32 s8, s8, 1
	s_cmp_lg_u32 s8, 0
	s_cbranch_scc1 .Lsc0_loop
	s_cmp_lt_u32 s9, 2
	s_cbranch_scc0 .Lsc0_w1sta
	s_waitcnt vmcnt(12)
	s_branch .Lsc0_w1eta

; #define SCAN_BAR()                                        \
;   {                                                       \
;     asm volatile("s_waitcnt lgkmcnt(0)" ::: "memory");     \
;     __builtin_amdgcn_s_barrier();                         \
;     asm volatile("" ::: "memory");                         \
;   }
; DEV void scan_item_mfma(const Params& p, int g, int item, char* smem) {
;     ...
;       if (wave < 2 && ci > 0) {
;         u16* og = PHG + (otok + 32 * wave + 4 * hh) * 2560 + ocol + r;
; #pragma unroll
;         for (int i = 0; i < 8; ++i) {
;           og[(size_t)(((2 * i) & 3) + 8 * ((2 * i) >> 2)) * 2560] = (u16)(opk[i] & 0xffffu);
;           og[(size_t)(((2 * i + 1) & 3) + 8 * ((2 * i + 1) >> 2)) * 2560] = (u16)(opk[i] >> 16);
;         }
;     ...
;     SCAN_BAR();
;   }
.Lsc1_p3efa:
	s_mov_b32 s0, 0x50000
	s_sub_u32 s22, s22, s0
	s_subb_u32 s23, s23, 0
	s_waitcnt lgkmcnt(0)
	s_barrier
	s_cmp_lt_u32 s9, 2
	s_cbranch_scc0 .Lsc1_w1sfb
	s_waitcnt vmcnt(10)
	s_branch .Lsc1_w1efb

; #define SCAN_BAR()                                        \
;   {                                                       \
;     asm volatile("s_waitcnt lgkmcnt(0)" ::: "memory");     \
;     __builtin_amdgcn_s_barrier();                         \
;     asm volatile("" ::: "memory");                         \
;   }
; DEV void scan_item_mfma(const Params& p, int g, int item, char* smem) {
;     ...
;   for (int ci = 0; ci < NC; ++ci) {
;     ...
;     SCAN_BAR();
;   }
.Lsc1_p3eb:
	s_mov_b32 s0, 0x50000
	s_sub_u32 s22, s22, s0
	s_subb_u32 s23, s23, 0
	s_waitcnt lgkmcnt(0)
	s_barrier
	s_sub_i32 s8, s8, 1
	s_cmp_lg_u32 s8, 0
	s_cbranch_scc1 .Lsc1_loop
	s_cmp_lt_u32 s9, 2
	s_cbranch_scc0 .Lsc1_w1sta
	s_waitcnt vmcnt(12)
	s_branch .Lsc1_w1eta
